# v41: v39 + drain of the weight-conversion ring's speculative loads before its registers are reused (the cause of the earlier x0 crash) + phase_x0 software-pipelined over two row register sets
# speedup vs baseline: 1.0067x; 1.0062x over previous
.Lcw_ret_23:
	s_waitcnt vmcnt(0) lgkmcnt(0)
	s_barrier
	s_branch .LBB0_99

.Lx0_fast:
	s_cmp_lg_u32 s46, 0x100
	s_cbranch_scc1 .LBB0_157
	global_load_dwordx4 v[18:21], v[8:9], off offset:-3072
	global_load_dwordx4 v[22:25], v[8:9], off offset:-2048
	global_load_dwordx4 v[26:29], v[8:9], off offset:-1024
	global_load_dwordx4 v[30:33], v[8:9], off
	v_lshl_add_u64 v[80:81], v[8:9], 0, s[18:19]
	global_load_dwordx4 v[64:67], v[80:81], off offset:-3072
	global_load_dwordx4 v[68:71], v[80:81], off offset:-2048
	global_load_dwordx4 v[72:75], v[80:81], off offset:-1024
	global_load_dwordx4 v[76:79], v[80:81], off
	s_waitcnt vmcnt(4)
	v_mul_f32_e32 v3, v19, v19
	s_waitcnt lgkmcnt(0)
	v_mul_f32_e32 v17, v23, v23
	v_mul_f32_e32 v34, v27, v27
	v_fmac_f32_e32 v3, v18, v18
	v_fmac_f32_e32 v17, v22, v22
	v_mul_f32_e32 v35, v31, v31
	v_fmac_f32_e32 v34, v26, v26
	v_fmac_f32_e32 v3, v20, v20
	v_fmac_f32_e32 v17, v24, v24
	v_fmac_f32_e32 v35, v30, v30
	v_fmac_f32_e32 v34, v28, v28
	v_fmac_f32_e32 v3, v21, v21
	v_fmac_f32_e32 v17, v25, v25
	v_fmac_f32_e32 v35, v32, v32
	v_fmac_f32_e32 v34, v29, v29
	v_add_f32_e32 v3, v3, v17
	v_fmac_f32_e32 v35, v33, v33
	v_add_f32_e32 v3, v3, v34
	v_add_f32_e32 v3, v3, v35
	ds_bpermute_b32 v17, v11, v3
	v_lshl_add_u64 v[34:35], s[10:11], 0, v[6:7]
	v_add_co_u32_e64 v34, s[0:1], s3, v34
	v_cvt_pk_bf16_f32 v18, v18, v19
	s_waitcnt lgkmcnt(0)
	v_add_f32_e32 v3, v3, v17
	ds_bpermute_b32 v17, v12, v3
	v_addc_co_u32_e64 v35, s[0:1], 0, v35, s[0:1]
	v_cvt_pk_bf16_f32 v19, v20, v21
	v_cvt_pk_bf16_f32 v20, v22, v23
	s_waitcnt lgkmcnt(0)
	v_add_f32_e32 v3, v3, v17
	ds_bpermute_b32 v17, v13, v3
	v_cvt_pk_bf16_f32 v21, v24, v25
	v_cvt_pk_bf16_f32 v22, v26, v27
	global_store_dwordx2 v[34:35], v[18:19], off
	global_store_dwordx2 v[34:35], v[20:21], off offset:512
	v_cvt_pk_bf16_f32 v23, v28, v29
	s_waitcnt lgkmcnt(0)
	v_add_f32_e32 v3, v3, v17
	ds_bpermute_b32 v17, v14, v3
	v_cvt_pk_bf16_f32 v18, v30, v31
	v_cvt_pk_bf16_f32 v19, v32, v33
	global_store_dwordx2 v[34:35], v[22:23], off offset:1024
	global_store_dwordx2 v[34:35], v[18:19], off offset:1536
	s_waitcnt lgkmcnt(0)
	v_add_f32_e32 v3, v3, v17
	ds_bpermute_b32 v17, v15, v3
	s_waitcnt lgkmcnt(0)
	v_add_f32_e32 v3, v3, v17
	ds_bpermute_b32 v17, v16, v3
	s_and_saveexec_b64 s[0:1], vcc
	s_waitcnt lgkmcnt(0)
	v_add_f32_e32 v3, v3, v17
	v_cndmask_b32_e64 v3, 0, v3, s[4:5]
	v_lshl_add_u64 v[18:19], s[10:11], 0, v[4:5]
	global_store_dword v[18:19], v3, off
	s_or_b64 exec, exec, s[0:1]
	v_lshl_add_u64 v[4:5], v[4:5], 0, s[14:15]
	v_lshl_add_u64 v[6:7], v[6:7], 0, s[16:17]
	v_lshl_add_u64 v[8:9], v[80:81], 0, s[18:19]
	global_load_dwordx4 v[18:21], v[8:9], off offset:-3072
	global_load_dwordx4 v[22:25], v[8:9], off offset:-2048
	global_load_dwordx4 v[26:29], v[8:9], off offset:-1024
	global_load_dwordx4 v[30:33], v[8:9], off
	s_waitcnt vmcnt(9)
	v_mul_f32_e32 v3, v65, v65
	s_waitcnt lgkmcnt(0)
	v_mul_f32_e32 v17, v69, v69
	v_mul_f32_e32 v34, v73, v73
	v_fmac_f32_e32 v3, v64, v64
	v_fmac_f32_e32 v17, v68, v68
	v_mul_f32_e32 v35, v77, v77
	v_fmac_f32_e32 v34, v72, v72
	v_fmac_f32_e32 v3, v66, v66
	v_fmac_f32_e32 v17, v70, v70
	v_fmac_f32_e32 v35, v76, v76
	v_fmac_f32_e32 v34, v74, v74
	v_fmac_f32_e32 v3, v67, v67
	v_fmac_f32_e32 v17, v71, v71
	v_fmac_f32_e32 v35, v78, v78
	v_fmac_f32_e32 v34, v75, v75
	v_add_f32_e32 v3, v3, v17
	v_fmac_f32_e32 v35, v79, v79
	v_add_f32_e32 v3, v3, v34
	v_add_f32_e32 v3, v3, v35
	ds_bpermute_b32 v17, v11, v3
	v_lshl_add_u64 v[34:35], s[10:11], 0, v[6:7]
	v_add_co_u32_e64 v34, s[0:1], s3, v34
	v_cvt_pk_bf16_f32 v64, v64, v65
	s_waitcnt lgkmcnt(0)
	v_add_f32_e32 v3, v3, v17
	ds_bpermute_b32 v17, v12, v3
	v_addc_co_u32_e64 v35, s[0:1], 0, v35, s[0:1]
	v_cvt_pk_bf16_f32 v65, v66, v67
	v_cvt_pk_bf16_f32 v66, v68, v69
	s_waitcnt lgkmcnt(0)
	v_add_f32_e32 v3, v3, v17
	ds_bpermute_b32 v17, v13, v3
	v_cvt_pk_bf16_f32 v67, v70, v71
	v_cvt_pk_bf16_f32 v68, v72, v73
	global_store_dwordx2 v[34:35], v[64:65], off
	global_store_dwordx2 v[34:35], v[66:67], off offset:512
	v_cvt_pk_bf16_f32 v69, v74, v75
	s_waitcnt lgkmcnt(0)
	v_add_f32_e32 v3, v3, v17
	ds_bpermute_b32 v17, v14, v3
	v_cvt_pk_bf16_f32 v64, v76, v77
	v_cvt_pk_bf16_f32 v65, v78, v79
	global_store_dwordx2 v[34:35], v[68:69], off offset:1024
	global_store_dwordx2 v[34:35], v[64:65], off offset:1536
	s_waitcnt lgkmcnt(0)
	v_add_f32_e32 v3, v3, v17
	ds_bpermute_b32 v17, v15, v3
	s_waitcnt lgkmcnt(0)
	v_add_f32_e32 v3, v3, v17
	ds_bpermute_b32 v17, v16, v3
	s_and_saveexec_b64 s[0:1], vcc
	s_waitcnt lgkmcnt(0)
	v_add_f32_e32 v3, v3, v17
	v_cndmask_b32_e64 v3, 0, v3, s[4:5]
	v_lshl_add_u64 v[64:65], s[10:11], 0, v[4:5]
	global_store_dword v[64:65], v3, off
	s_or_b64 exec, exec, s[0:1]
	v_lshl_add_u64 v[4:5], v[4:5], 0, s[14:15]
	v_lshl_add_u64 v[6:7], v[6:7], 0, s[16:17]
	v_lshl_add_u64 v[80:81], v[8:9], 0, s[18:19]
	global_load_dwordx4 v[64:67], v[80:81], off offset:-3072
	global_load_dwordx4 v[68:71], v[80:81], off offset:-2048
	global_load_dwordx4 v[72:75], v[80:81], off offset:-1024
	global_load_dwordx4 v[76:79], v[80:81], off
	s_waitcnt vmcnt(9)
	v_mul_f32_e32 v3, v19, v19
	s_waitcnt lgkmcnt(0)
	v_mul_f32_e32 v17, v23, v23
	v_mul_f32_e32 v34, v27, v27
	v_fmac_f32_e32 v3, v18, v18
	v_fmac_f32_e32 v17, v22, v22
	v_mul_f32_e32 v35, v31, v31
	v_fmac_f32_e32 v34, v26, v26
	v_fmac_f32_e32 v3, v20, v20
	v_fmac_f32_e32 v17, v24, v24
	v_fmac_f32_e32 v35, v30, v30
	v_fmac_f32_e32 v34, v28, v28
	v_fmac_f32_e32 v3, v21, v21
	v_fmac_f32_e32 v17, v25, v25
	v_fmac_f32_e32 v35, v32, v32
	v_fmac_f32_e32 v34, v29, v29
	v_add_f32_e32 v3, v3, v17
	v_fmac_f32_e32 v35, v33, v33
	v_add_f32_e32 v3, v3, v34
	v_add_f32_e32 v3, v3, v35
	ds_bpermute_b32 v17, v11, v3
	v_lshl_add_u64 v[34:35], s[10:11], 0, v[6:7]
	v_add_co_u32_e64 v34, s[0:1], s3, v34
	v_cvt_pk_bf16_f32 v18, v18, v19
	s_waitcnt lgkmcnt(0)
	v_add_f32_e32 v3, v3, v17
	ds_bpermute_b32 v17, v12, v3
	v_addc_co_u32_e64 v35, s[0:1], 0, v35, s[0:1]
	v_cvt_pk_bf16_f32 v19, v20, v21
	v_cvt_pk_bf16_f32 v20, v22, v23
	s_waitcnt lgkmcnt(0)
	v_add_f32_e32 v3, v3, v17
	ds_bpermute_b32 v17, v13, v3
	v_cvt_pk_bf16_f32 v21, v24, v25
	v_cvt_pk_bf16_f32 v22, v26, v27
	global_store_dwordx2 v[34:35], v[18:19], off
	global_store_dwordx2 v[34:35], v[20:21], off offset:512
	v_cvt_pk_bf16_f32 v23, v28, v29
	s_waitcnt lgkmcnt(0)
	v_add_f32_e32 v3, v3, v17
	ds_bpermute_b32 v17, v14, v3
	v_cvt_pk_bf16_f32 v18, v30, v31
	v_cvt_pk_bf16_f32 v19, v32, v33
	global_store_dwordx2 v[34:35], v[22:23], off offset:1024
	global_store_dwordx2 v[34:35], v[18:19], off offset:1536
	s_waitcnt lgkmcnt(0)
	v_add_f32_e32 v3, v3, v17
	ds_bpermute_b32 v17, v15, v3
	s_waitcnt lgkmcnt(0)
	v_add_f32_e32 v3, v3, v17
	ds_bpermute_b32 v17, v16, v3
	s_and_saveexec_b64 s[0:1], vcc
	s_waitcnt lgkmcnt(0)
	v_add_f32_e32 v3, v3, v17
	v_cndmask_b32_e64 v3, 0, v3, s[4:5]
	v_lshl_add_u64 v[18:19], s[10:11], 0, v[4:5]
	global_store_dword v[18:19], v3, off
	s_or_b64 exec, exec, s[0:1]
	v_lshl_add_u64 v[4:5], v[4:5], 0, s[14:15]
	v_lshl_add_u64 v[6:7], v[6:7], 0, s[16:17]
	v_lshl_add_u64 v[8:9], v[80:81], 0, s[18:19]
	global_load_dwordx4 v[18:21], v[8:9], off offset:-3072
	global_load_dwordx4 v[22:25], v[8:9], off offset:-2048
	global_load_dwordx4 v[26:29], v[8:9], off offset:-1024
	global_load_dwordx4 v[30:33], v[8:9], off
	s_waitcnt vmcnt(9)
	v_mul_f32_e32 v3, v65, v65
	s_waitcnt lgkmcnt(0)
	v_mul_f32_e32 v17, v69, v69
	v_mul_f32_e32 v34, v73, v73
	v_fmac_f32_e32 v3, v64, v64
	v_fmac_f32_e32 v17, v68, v68
	v_mul_f32_e32 v35, v77, v77
	v_fmac_f32_e32 v34, v72, v72
	v_fmac_f32_e32 v3, v66, v66
	v_fmac_f32_e32 v17, v70, v70
	v_fmac_f32_e32 v35, v76, v76
	v_fmac_f32_e32 v34, v74, v74
	v_fmac_f32_e32 v3, v67, v67
	v_fmac_f32_e32 v17, v71, v71
	v_fmac_f32_e32 v35, v78, v78
	v_fmac_f32_e32 v34, v75, v75
	v_add_f32_e32 v3, v3, v17
	v_fmac_f32_e32 v35, v79, v79
	v_add_f32_e32 v3, v3, v34
	v_add_f32_e32 v3, v3, v35
	ds_bpermute_b32 v17, v11, v3
	v_lshl_add_u64 v[34:35], s[10:11], 0, v[6:7]
	v_add_co_u32_e64 v34, s[0:1], s3, v34
	v_cvt_pk_bf16_f32 v64, v64, v65
	s_waitcnt lgkmcnt(0)
	v_add_f32_e32 v3, v3, v17
	ds_bpermute_b32 v17, v12, v3
	v_addc_co_u32_e64 v35, s[0:1], 0, v35, s[0:1]
	v_cvt_pk_bf16_f32 v65, v66, v67
	v_cvt_pk_bf16_f32 v66, v68, v69
	s_waitcnt lgkmcnt(0)
	v_add_f32_e32 v3, v3, v17
	ds_bpermute_b32 v17, v13, v3
	v_cvt_pk_bf16_f32 v67, v70, v71
	v_cvt_pk_bf16_f32 v68, v72, v73
	global_store_dwordx2 v[34:35], v[64:65], off
	global_store_dwordx2 v[34:35], v[66:67], off offset:512
	v_cvt_pk_bf16_f32 v69, v74, v75
	s_waitcnt lgkmcnt(0)
	v_add_f32_e32 v3, v3, v17
	ds_bpermute_b32 v17, v14, v3
	v_cvt_pk_bf16_f32 v64, v76, v77
	v_cvt_pk_bf16_f32 v65, v78, v79
	global_store_dwordx2 v[34:35], v[68:69], off offset:1024
	global_store_dwordx2 v[34:35], v[64:65], off offset:1536
	s_waitcnt lgkmcnt(0)
	v_add_f32_e32 v3, v3, v17
	ds_bpermute_b32 v17, v15, v3
	s_waitcnt lgkmcnt(0)
	v_add_f32_e32 v3, v3, v17
	ds_bpermute_b32 v17, v16, v3
	s_and_saveexec_b64 s[0:1], vcc
	s_waitcnt lgkmcnt(0)
	v_add_f32_e32 v3, v3, v17
	v_cndmask_b32_e64 v3, 0, v3, s[4:5]
	v_lshl_add_u64 v[64:65], s[10:11], 0, v[4:5]
	global_store_dword v[64:65], v3, off
	s_or_b64 exec, exec, s[0:1]
	v_lshl_add_u64 v[4:5], v[4:5], 0, s[14:15]
	v_lshl_add_u64 v[6:7], v[6:7], 0, s[16:17]
	v_lshl_add_u64 v[80:81], v[8:9], 0, s[18:19]
	global_load_dwordx4 v[64:67], v[80:81], off offset:-3072
	global_load_dwordx4 v[68:71], v[80:81], off offset:-2048
	global_load_dwordx4 v[72:75], v[80:81], off offset:-1024
	global_load_dwordx4 v[76:79], v[80:81], off
	s_waitcnt vmcnt(9)
	v_mul_f32_e32 v3, v19, v19
	s_waitcnt lgkmcnt(0)
	v_mul_f32_e32 v17, v23, v23
	v_mul_f32_e32 v34, v27, v27
	v_fmac_f32_e32 v3, v18, v18
	v_fmac_f32_e32 v17, v22, v22
	v_mul_f32_e32 v35, v31, v31
	v_fmac_f32_e32 v34, v26, v26
	v_fmac_f32_e32 v3, v20, v20
	v_fmac_f32_e32 v17, v24, v24
	v_fmac_f32_e32 v35, v30, v30
	v_fmac_f32_e32 v34, v28, v28
	v_fmac_f32_e32 v3, v21, v21
	v_fmac_f32_e32 v17, v25, v25
	v_fmac_f32_e32 v35, v32, v32
	v_fmac_f32_e32 v34, v29, v29
	v_add_f32_e32 v3, v3, v17
	v_fmac_f32_e32 v35, v33, v33
	v_add_f32_e32 v3, v3, v34
	v_add_f32_e32 v3, v3, v35
	ds_bpermute_b32 v17, v11, v3
	v_lshl_add_u64 v[34:35], s[10:11], 0, v[6:7]
	v_add_co_u32_e64 v34, s[0:1], s3, v34
	v_cvt_pk_bf16_f32 v18, v18, v19
	s_waitcnt lgkmcnt(0)
	v_add_f32_e32 v3, v3, v17
	ds_bpermute_b32 v17, v12, v3
	v_addc_co_u32_e64 v35, s[0:1], 0, v35, s[0:1]
	v_cvt_pk_bf16_f32 v19, v20, v21
	v_cvt_pk_bf16_f32 v20, v22, v23
	s_waitcnt lgkmcnt(0)
	v_add_f32_e32 v3, v3, v17
	ds_bpermute_b32 v17, v13, v3
	v_cvt_pk_bf16_f32 v21, v24, v25
	v_cvt_pk_bf16_f32 v22, v26, v27
	global_store_dwordx2 v[34:35], v[18:19], off
	global_store_dwordx2 v[34:35], v[20:21], off offset:512
	v_cvt_pk_bf16_f32 v23, v28, v29
	s_waitcnt lgkmcnt(0)
	v_add_f32_e32 v3, v3, v17
	ds_bpermute_b32 v17, v14, v3
	v_cvt_pk_bf16_f32 v18, v30, v31
	v_cvt_pk_bf16_f32 v19, v32, v33
	global_store_dwordx2 v[34:35], v[22:23], off offset:1024
	global_store_dwordx2 v[34:35], v[18:19], off offset:1536
	s_waitcnt lgkmcnt(0)
	v_add_f32_e32 v3, v3, v17
	ds_bpermute_b32 v17, v15, v3
	s_waitcnt lgkmcnt(0)
	v_add_f32_e32 v3, v3, v17
	ds_bpermute_b32 v17, v16, v3
	s_and_saveexec_b64 s[0:1], vcc
	s_waitcnt lgkmcnt(0)
	v_add_f32_e32 v3, v3, v17
	v_cndmask_b32_e64 v3, 0, v3, s[4:5]
	v_lshl_add_u64 v[18:19], s[10:11], 0, v[4:5]
	global_store_dword v[18:19], v3, off
	s_or_b64 exec, exec, s[0:1]
	v_lshl_add_u64 v[4:5], v[4:5], 0, s[14:15]
	v_lshl_add_u64 v[6:7], v[6:7], 0, s[16:17]
	v_lshl_add_u64 v[8:9], v[80:81], 0, s[18:19]
	global_load_dwordx4 v[18:21], v[8:9], off offset:-3072
	global_load_dwordx4 v[22:25], v[8:9], off offset:-2048
	global_load_dwordx4 v[26:29], v[8:9], off offset:-1024
	global_load_dwordx4 v[30:33], v[8:9], off
	s_waitcnt vmcnt(9)
	v_mul_f32_e32 v3, v65, v65
	s_waitcnt lgkmcnt(0)
	v_mul_f32_e32 v17, v69, v69
	v_mul_f32_e32 v34, v73, v73
	v_fmac_f32_e32 v3, v64, v64
	v_fmac_f32_e32 v17, v68, v68
	v_mul_f32_e32 v35, v77, v77
	v_fmac_f32_e32 v34, v72, v72
	v_fmac_f32_e32 v3, v66, v66
	v_fmac_f32_e32 v17, v70, v70
	v_fmac_f32_e32 v35, v76, v76
	v_fmac_f32_e32 v34, v74, v74
	v_fmac_f32_e32 v3, v67, v67
	v_fmac_f32_e32 v17, v71, v71
	v_fmac_f32_e32 v35, v78, v78
	v_fmac_f32_e32 v34, v75, v75
	v_add_f32_e32 v3, v3, v17
	v_fmac_f32_e32 v35, v79, v79
	v_add_f32_e32 v3, v3, v34
	v_add_f32_e32 v3, v3, v35
	ds_bpermute_b32 v17, v11, v3
	v_lshl_add_u64 v[34:35], s[10:11], 0, v[6:7]
	v_add_co_u32_e64 v34, s[0:1], s3, v34
	v_cvt_pk_bf16_f32 v64, v64, v65
	s_waitcnt lgkmcnt(0)
	v_add_f32_e32 v3, v3, v17
	ds_bpermute_b32 v17, v12, v3
	v_addc_co_u32_e64 v35, s[0:1], 0, v35, s[0:1]
	v_cvt_pk_bf16_f32 v65, v66, v67
	v_cvt_pk_bf16_f32 v66, v68, v69
	s_waitcnt lgkmcnt(0)
	v_add_f32_e32 v3, v3, v17
	ds_bpermute_b32 v17, v13, v3
	v_cvt_pk_bf16_f32 v67, v70, v71
	v_cvt_pk_bf16_f32 v68, v72, v73
	global_store_dwordx2 v[34:35], v[64:65], off
	global_store_dwordx2 v[34:35], v[66:67], off offset:512
	v_cvt_pk_bf16_f32 v69, v74, v75
	s_waitcnt lgkmcnt(0)
	v_add_f32_e32 v3, v3, v17
	ds_bpermute_b32 v17, v14, v3
	v_cvt_pk_bf16_f32 v64, v76, v77
	v_cvt_pk_bf16_f32 v65, v78, v79
	global_store_dwordx2 v[34:35], v[68:69], off offset:1024
	global_store_dwordx2 v[34:35], v[64:65], off offset:1536
	s_waitcnt lgkmcnt(0)
	v_add_f32_e32 v3, v3, v17
	ds_bpermute_b32 v17, v15, v3
	s_waitcnt lgkmcnt(0)
	v_add_f32_e32 v3, v3, v17
	ds_bpermute_b32 v17, v16, v3
	s_and_saveexec_b64 s[0:1], vcc
	s_waitcnt lgkmcnt(0)
	v_add_f32_e32 v3, v3, v17
	v_cndmask_b32_e64 v3, 0, v3, s[4:5]
	v_lshl_add_u64 v[64:65], s[10:11], 0, v[4:5]
	global_store_dword v[64:65], v3, off
	s_or_b64 exec, exec, s[0:1]
	v_lshl_add_u64 v[4:5], v[4:5], 0, s[14:15]
	v_lshl_add_u64 v[6:7], v[6:7], 0, s[16:17]
	v_lshl_add_u64 v[80:81], v[8:9], 0, s[18:19]
	global_load_dwordx4 v[64:67], v[80:81], off offset:-3072
	global_load_dwordx4 v[68:71], v[80:81], off offset:-2048
	global_load_dwordx4 v[72:75], v[80:81], off offset:-1024
	global_load_dwordx4 v[76:79], v[80:81], off
	s_waitcnt vmcnt(9)
	v_mul_f32_e32 v3, v19, v19
	s_waitcnt lgkmcnt(0)
	v_mul_f32_e32 v17, v23, v23
	v_mul_f32_e32 v34, v27, v27
	v_fmac_f32_e32 v3, v18, v18
	v_fmac_f32_e32 v17, v22, v22
	v_mul_f32_e32 v35, v31, v31
	v_fmac_f32_e32 v34, v26, v26
	v_fmac_f32_e32 v3, v20, v20
	v_fmac_f32_e32 v17, v24, v24
	v_fmac_f32_e32 v35, v30, v30
	v_fmac_f32_e32 v34, v28, v28
	v_fmac_f32_e32 v3, v21, v21
	v_fmac_f32_e32 v17, v25, v25
	v_fmac_f32_e32 v35, v32, v32
	v_fmac_f32_e32 v34, v29, v29
	v_add_f32_e32 v3, v3, v17
	v_fmac_f32_e32 v35, v33, v33
	v_add_f32_e32 v3, v3, v34
	v_add_f32_e32 v3, v3, v35
	ds_bpermute_b32 v17, v11, v3
	v_lshl_add_u64 v[34:35], s[10:11], 0, v[6:7]
	v_add_co_u32_e64 v34, s[0:1], s3, v34
	v_cvt_pk_bf16_f32 v18, v18, v19
	s_waitcnt lgkmcnt(0)
	v_add_f32_e32 v3, v3, v17
	ds_bpermute_b32 v17, v12, v3
	v_addc_co_u32_e64 v35, s[0:1], 0, v35, s[0:1]
	v_cvt_pk_bf16_f32 v19, v20, v21
	v_cvt_pk_bf16_f32 v20, v22, v23
	s_waitcnt lgkmcnt(0)
	v_add_f32_e32 v3, v3, v17
	ds_bpermute_b32 v17, v13, v3
	v_cvt_pk_bf16_f32 v21, v24, v25
	v_cvt_pk_bf16_f32 v22, v26, v27
	global_store_dwordx2 v[34:35], v[18:19], off
	global_store_dwordx2 v[34:35], v[20:21], off offset:512
	v_cvt_pk_bf16_f32 v23, v28, v29
	s_waitcnt lgkmcnt(0)
	v_add_f32_e32 v3, v3, v17
	ds_bpermute_b32 v17, v14, v3
	v_cvt_pk_bf16_f32 v18, v30, v31
	v_cvt_pk_bf16_f32 v19, v32, v33
	global_store_dwordx2 v[34:35], v[22:23], off offset:1024
	global_store_dwordx2 v[34:35], v[18:19], off offset:1536
	s_waitcnt lgkmcnt(0)
	v_add_f32_e32 v3, v3, v17
	ds_bpermute_b32 v17, v15, v3
	s_waitcnt lgkmcnt(0)
	v_add_f32_e32 v3, v3, v17
	ds_bpermute_b32 v17, v16, v3
	s_and_saveexec_b64 s[0:1], vcc
	s_waitcnt lgkmcnt(0)
	v_add_f32_e32 v3, v3, v17
	v_cndmask_b32_e64 v3, 0, v3, s[4:5]
	v_lshl_add_u64 v[18:19], s[10:11], 0, v[4:5]
	global_store_dword v[18:19], v3, off
	s_or_b64 exec, exec, s[0:1]
	v_lshl_add_u64 v[4:5], v[4:5], 0, s[14:15]
	v_lshl_add_u64 v[6:7], v[6:7], 0, s[16:17]
	v_lshl_add_u64 v[8:9], v[80:81], 0, s[18:19]
	global_load_dwordx4 v[18:21], v[8:9], off offset:-3072
	global_load_dwordx4 v[22:25], v[8:9], off offset:-2048
	global_load_dwordx4 v[26:29], v[8:9], off offset:-1024
	global_load_dwordx4 v[30:33], v[8:9], off
	s_waitcnt vmcnt(9)
	v_mul_f32_e32 v3, v65, v65
	s_waitcnt lgkmcnt(0)
	v_mul_f32_e32 v17, v69, v69
	v_mul_f32_e32 v34, v73, v73
	v_fmac_f32_e32 v3, v64, v64
	v_fmac_f32_e32 v17, v68, v68
	v_mul_f32_e32 v35, v77, v77
	v_fmac_f32_e32 v34, v72, v72
	v_fmac_f32_e32 v3, v66, v66
	v_fmac_f32_e32 v17, v70, v70
	v_fmac_f32_e32 v35, v76, v76
	v_fmac_f32_e32 v34, v74, v74
	v_fmac_f32_e32 v3, v67, v67
	v_fmac_f32_e32 v17, v71, v71
	v_fmac_f32_e32 v35, v78, v78
	v_fmac_f32_e32 v34, v75, v75
	v_add_f32_e32 v3, v3, v17
	v_fmac_f32_e32 v35, v79, v79
	v_add_f32_e32 v3, v3, v34
	v_add_f32_e32 v3, v3, v35
	ds_bpermute_b32 v17, v11, v3
	v_lshl_add_u64 v[34:35], s[10:11], 0, v[6:7]
	v_add_co_u32_e64 v34, s[0:1], s3, v34
	v_cvt_pk_bf16_f32 v64, v64, v65
	s_waitcnt lgkmcnt(0)
	v_add_f32_e32 v3, v3, v17
	ds_bpermute_b32 v17, v12, v3
	v_addc_co_u32_e64 v35, s[0:1], 0, v35, s[0:1]
	v_cvt_pk_bf16_f32 v65, v66, v67
	v_cvt_pk_bf16_f32 v66, v68, v69
	s_waitcnt lgkmcnt(0)
	v_add_f32_e32 v3, v3, v17
	ds_bpermute_b32 v17, v13, v3
	v_cvt_pk_bf16_f32 v67, v70, v71
	v_cvt_pk_bf16_f32 v68, v72, v73
	global_store_dwordx2 v[34:35], v[64:65], off
	global_store_dwordx2 v[34:35], v[66:67], off offset:512
	v_cvt_pk_bf16_f32 v69, v74, v75
	s_waitcnt lgkmcnt(0)
	v_add_f32_e32 v3, v3, v17
	ds_bpermute_b32 v17, v14, v3
	v_cvt_pk_bf16_f32 v64, v76, v77
	v_cvt_pk_bf16_f32 v65, v78, v79
	global_store_dwordx2 v[34:35], v[68:69], off offset:1024
	global_store_dwordx2 v[34:35], v[64:65], off offset:1536
	s_waitcnt lgkmcnt(0)
	v_add_f32_e32 v3, v3, v17
	ds_bpermute_b32 v17, v15, v3
	s_waitcnt lgkmcnt(0)
	v_add_f32_e32 v3, v3, v17
	ds_bpermute_b32 v17, v16, v3
	s_and_saveexec_b64 s[0:1], vcc
	s_waitcnt lgkmcnt(0)
	v_add_f32_e32 v3, v3, v17
	v_cndmask_b32_e64 v3, 0, v3, s[4:5]
	v_lshl_add_u64 v[64:65], s[10:11], 0, v[4:5]
	global_store_dword v[64:65], v3, off
	s_or_b64 exec, exec, s[0:1]
	v_lshl_add_u64 v[4:5], v[4:5], 0, s[14:15]
	v_lshl_add_u64 v[6:7], v[6:7], 0, s[16:17]
	v_lshl_add_u64 v[80:81], v[8:9], 0, s[18:19]
	global_load_dwordx4 v[64:67], v[80:81], off offset:-3072
	global_load_dwordx4 v[68:71], v[80:81], off offset:-2048
	global_load_dwordx4 v[72:75], v[80:81], off offset:-1024
	global_load_dwordx4 v[76:79], v[80:81], off
	s_waitcnt vmcnt(9)
	v_mul_f32_e32 v3, v19, v19
	s_waitcnt lgkmcnt(0)
	v_mul_f32_e32 v17, v23, v23
	v_mul_f32_e32 v34, v27, v27
	v_fmac_f32_e32 v3, v18, v18
	v_fmac_f32_e32 v17, v22, v22
	v_mul_f32_e32 v35, v31, v31
	v_fmac_f32_e32 v34, v26, v26
	v_fmac_f32_e32 v3, v20, v20
	v_fmac_f32_e32 v17, v24, v24
	v_fmac_f32_e32 v35, v30, v30
	v_fmac_f32_e32 v34, v28, v28
	v_fmac_f32_e32 v3, v21, v21
	v_fmac_f32_e32 v17, v25, v25
	v_fmac_f32_e32 v35, v32, v32
	v_fmac_f32_e32 v34, v29, v29
	v_add_f32_e32 v3, v3, v17
	v_fmac_f32_e32 v35, v33, v33
	v_add_f32_e32 v3, v3, v34
	v_add_f32_e32 v3, v3, v35
	ds_bpermute_b32 v17, v11, v3
	v_lshl_add_u64 v[34:35], s[10:11], 0, v[6:7]
	v_add_co_u32_e64 v34, s[0:1], s3, v34
	v_cvt_pk_bf16_f32 v18, v18, v19
	s_waitcnt lgkmcnt(0)
	v_add_f32_e32 v3, v3, v17
	ds_bpermute_b32 v17, v12, v3
	v_addc_co_u32_e64 v35, s[0:1], 0, v35, s[0:1]
	v_cvt_pk_bf16_f32 v19, v20, v21
	v_cvt_pk_bf16_f32 v20, v22, v23
	s_waitcnt lgkmcnt(0)
	v_add_f32_e32 v3, v3, v17
	ds_bpermute_b32 v17, v13, v3
	v_cvt_pk_bf16_f32 v21, v24, v25
	v_cvt_pk_bf16_f32 v22, v26, v27
	global_store_dwordx2 v[34:35], v[18:19], off
	global_store_dwordx2 v[34:35], v[20:21], off offset:512
	v_cvt_pk_bf16_f32 v23, v28, v29
	s_waitcnt lgkmcnt(0)
	v_add_f32_e32 v3, v3, v17
	ds_bpermute_b32 v17, v14, v3
	v_cvt_pk_bf16_f32 v18, v30, v31
	v_cvt_pk_bf16_f32 v19, v32, v33
	global_store_dwordx2 v[34:35], v[22:23], off offset:1024
	global_store_dwordx2 v[34:35], v[18:19], off offset:1536
	s_waitcnt lgkmcnt(0)
	v_add_f32_e32 v3, v3, v17
	ds_bpermute_b32 v17, v15, v3
	s_waitcnt lgkmcnt(0)
	v_add_f32_e32 v3, v3, v17
	ds_bpermute_b32 v17, v16, v3
	s_and_saveexec_b64 s[0:1], vcc
	s_waitcnt lgkmcnt(0)
	v_add_f32_e32 v3, v3, v17
	v_cndmask_b32_e64 v3, 0, v3, s[4:5]
	v_lshl_add_u64 v[18:19], s[10:11], 0, v[4:5]
	global_store_dword v[18:19], v3, off
	s_or_b64 exec, exec, s[0:1]
	v_lshl_add_u64 v[4:5], v[4:5], 0, s[14:15]
	v_lshl_add_u64 v[6:7], v[6:7], 0, s[16:17]
	v_lshl_add_u64 v[8:9], v[80:81], 0, s[18:19]
	global_load_dwordx4 v[18:21], v[8:9], off offset:-3072
	global_load_dwordx4 v[22:25], v[8:9], off offset:-2048
	global_load_dwordx4 v[26:29], v[8:9], off offset:-1024
	global_load_dwordx4 v[30:33], v[8:9], off
	s_waitcnt vmcnt(9)
	v_mul_f32_e32 v3, v65, v65
	s_waitcnt lgkmcnt(0)
	v_mul_f32_e32 v17, v69, v69
	v_mul_f32_e32 v34, v73, v73
	v_fmac_f32_e32 v3, v64, v64
	v_fmac_f32_e32 v17, v68, v68
	v_mul_f32_e32 v35, v77, v77
	v_fmac_f32_e32 v34, v72, v72
	v_fmac_f32_e32 v3, v66, v66
	v_fmac_f32_e32 v17, v70, v70
	v_fmac_f32_e32 v35, v76, v76
	v_fmac_f32_e32 v34, v74, v74
	v_fmac_f32_e32 v3, v67, v67
	v_fmac_f32_e32 v17, v71, v71
	v_fmac_f32_e32 v35, v78, v78
	v_fmac_f32_e32 v34, v75, v75
	v_add_f32_e32 v3, v3, v17
	v_fmac_f32_e32 v35, v79, v79
	v_add_f32_e32 v3, v3, v34
	v_add_f32_e32 v3, v3, v35
	ds_bpermute_b32 v17, v11, v3
	v_lshl_add_u64 v[34:35], s[10:11], 0, v[6:7]
	v_add_co_u32_e64 v34, s[0:1], s3, v34
	v_cvt_pk_bf16_f32 v64, v64, v65
	s_waitcnt lgkmcnt(0)
	v_add_f32_e32 v3, v3, v17
	ds_bpermute_b32 v17, v12, v3
	v_addc_co_u32_e64 v35, s[0:1], 0, v35, s[0:1]
	v_cvt_pk_bf16_f32 v65, v66, v67
	v_cvt_pk_bf16_f32 v66, v68, v69
	s_waitcnt lgkmcnt(0)
	v_add_f32_e32 v3, v3, v17
	ds_bpermute_b32 v17, v13, v3
	v_cvt_pk_bf16_f32 v67, v70, v71
	v_cvt_pk_bf16_f32 v68, v72, v73
	global_store_dwordx2 v[34:35], v[64:65], off
	global_store_dwordx2 v[34:35], v[66:67], off offset:512
	v_cvt_pk_bf16_f32 v69, v74, v75
	s_waitcnt lgkmcnt(0)
	v_add_f32_e32 v3, v3, v17
	ds_bpermute_b32 v17, v14, v3
	v_cvt_pk_bf16_f32 v64, v76, v77
	v_cvt_pk_bf16_f32 v65, v78, v79
	global_store_dwordx2 v[34:35], v[68:69], off offset:1024
	global_store_dwordx2 v[34:35], v[64:65], off offset:1536
	s_waitcnt lgkmcnt(0)
	v_add_f32_e32 v3, v3, v17
	ds_bpermute_b32 v17, v15, v3
	s_waitcnt lgkmcnt(0)
	v_add_f32_e32 v3, v3, v17
	ds_bpermute_b32 v17, v16, v3
	s_and_saveexec_b64 s[0:1], vcc
	s_waitcnt lgkmcnt(0)
	v_add_f32_e32 v3, v3, v17
	v_cndmask_b32_e64 v3, 0, v3, s[4:5]
	v_lshl_add_u64 v[64:65], s[10:11], 0, v[4:5]
	global_store_dword v[64:65], v3, off
	s_or_b64 exec, exec, s[0:1]
	v_lshl_add_u64 v[4:5], v[4:5], 0, s[14:15]
	v_lshl_add_u64 v[6:7], v[6:7], 0, s[16:17]
	v_lshl_add_u64 v[80:81], v[8:9], 0, s[18:19]
	global_load_dwordx4 v[64:67], v[80:81], off offset:-3072
	global_load_dwordx4 v[68:71], v[80:81], off offset:-2048
	global_load_dwordx4 v[72:75], v[80:81], off offset:-1024
	global_load_dwordx4 v[76:79], v[80:81], off
	s_waitcnt vmcnt(9)
	v_mul_f32_e32 v3, v19, v19
	s_waitcnt lgkmcnt(0)
	v_mul_f32_e32 v17, v23, v23
	v_mul_f32_e32 v34, v27, v27
	v_fmac_f32_e32 v3, v18, v18
	v_fmac_f32_e32 v17, v22, v22
	v_mul_f32_e32 v35, v31, v31
	v_fmac_f32_e32 v34, v26, v26
	v_fmac_f32_e32 v3, v20, v20
	v_fmac_f32_e32 v17, v24, v24
	v_fmac_f32_e32 v35, v30, v30
	v_fmac_f32_e32 v34, v28, v28
	v_fmac_f32_e32 v3, v21, v21
	v_fmac_f32_e32 v17, v25, v25
	v_fmac_f32_e32 v35, v32, v32
	v_fmac_f32_e32 v34, v29, v29
	v_add_f32_e32 v3, v3, v17
	v_fmac_f32_e32 v35, v33, v33
	v_add_f32_e32 v3, v3, v34
	v_add_f32_e32 v3, v3, v35
	ds_bpermute_b32 v17, v11, v3
	v_lshl_add_u64 v[34:35], s[10:11], 0, v[6:7]
	v_add_co_u32_e64 v34, s[0:1], s3, v34
	v_cvt_pk_bf16_f32 v18, v18, v19
	s_waitcnt lgkmcnt(0)
	v_add_f32_e32 v3, v3, v17
	ds_bpermute_b32 v17, v12, v3
	v_addc_co_u32_e64 v35, s[0:1], 0, v35, s[0:1]
	v_cvt_pk_bf16_f32 v19, v20, v21
	v_cvt_pk_bf16_f32 v20, v22, v23
	s_waitcnt lgkmcnt(0)
	v_add_f32_e32 v3, v3, v17
	ds_bpermute_b32 v17, v13, v3
	v_cvt_pk_bf16_f32 v21, v24, v25
	v_cvt_pk_bf16_f32 v22, v26, v27
	global_store_dwordx2 v[34:35], v[18:19], off
	global_store_dwordx2 v[34:35], v[20:21], off offset:512
	v_cvt_pk_bf16_f32 v23, v28, v29
	s_waitcnt lgkmcnt(0)
	v_add_f32_e32 v3, v3, v17
	ds_bpermute_b32 v17, v14, v3
	v_cvt_pk_bf16_f32 v18, v30, v31
	v_cvt_pk_bf16_f32 v19, v32, v33
	global_store_dwordx2 v[34:35], v[22:23], off offset:1024
	global_store_dwordx2 v[34:35], v[18:19], off offset:1536
	s_waitcnt lgkmcnt(0)
	v_add_f32_e32 v3, v3, v17
	ds_bpermute_b32 v17, v15, v3
	s_waitcnt lgkmcnt(0)
	v_add_f32_e32 v3, v3, v17
	ds_bpermute_b32 v17, v16, v3
	s_and_saveexec_b64 s[0:1], vcc
	s_waitcnt lgkmcnt(0)
	v_add_f32_e32 v3, v3, v17
	v_cndmask_b32_e64 v3, 0, v3, s[4:5]
	v_lshl_add_u64 v[18:19], s[10:11], 0, v[4:5]
	global_store_dword v[18:19], v3, off
	s_or_b64 exec, exec, s[0:1]
	v_lshl_add_u64 v[4:5], v[4:5], 0, s[14:15]
	v_lshl_add_u64 v[6:7], v[6:7], 0, s[16:17]
	v_lshl_add_u64 v[8:9], v[80:81], 0, s[18:19]
	global_load_dwordx4 v[18:21], v[8:9], off offset:-3072
	global_load_dwordx4 v[22:25], v[8:9], off offset:-2048
	global_load_dwordx4 v[26:29], v[8:9], off offset:-1024
	global_load_dwordx4 v[30:33], v[8:9], off
	s_waitcnt vmcnt(9)
	v_mul_f32_e32 v3, v65, v65
	s_waitcnt lgkmcnt(0)
	v_mul_f32_e32 v17, v69, v69
	v_mul_f32_e32 v34, v73, v73
	v_fmac_f32_e32 v3, v64, v64
	v_fmac_f32_e32 v17, v68, v68
	v_mul_f32_e32 v35, v77, v77
	v_fmac_f32_e32 v34, v72, v72
	v_fmac_f32_e32 v3, v66, v66
	v_fmac_f32_e32 v17, v70, v70
	v_fmac_f32_e32 v35, v76, v76
	v_fmac_f32_e32 v34, v74, v74
	v_fmac_f32_e32 v3, v67, v67
	v_fmac_f32_e32 v17, v71, v71
	v_fmac_f32_e32 v35, v78, v78
	v_fmac_f32_e32 v34, v75, v75
	v_add_f32_e32 v3, v3, v17
	v_fmac_f32_e32 v35, v79, v79
	v_add_f32_e32 v3, v3, v34
	v_add_f32_e32 v3, v3, v35
	ds_bpermute_b32 v17, v11, v3
	v_lshl_add_u64 v[34:35], s[10:11], 0, v[6:7]
	v_add_co_u32_e64 v34, s[0:1], s3, v34
	v_cvt_pk_bf16_f32 v64, v64, v65
	s_waitcnt lgkmcnt(0)
	v_add_f32_e32 v3, v3, v17
	ds_bpermute_b32 v17, v12, v3
	v_addc_co_u32_e64 v35, s[0:1], 0, v35, s[0:1]
	v_cvt_pk_bf16_f32 v65, v66, v67
	v_cvt_pk_bf16_f32 v66, v68, v69
	s_waitcnt lgkmcnt(0)
	v_add_f32_e32 v3, v3, v17
	ds_bpermute_b32 v17, v13, v3
	v_cvt_pk_bf16_f32 v67, v70, v71
	v_cvt_pk_bf16_f32 v68, v72, v73
	global_store_dwordx2 v[34:35], v[64:65], off
	global_store_dwordx2 v[34:35], v[66:67], off offset:512
	v_cvt_pk_bf16_f32 v69, v74, v75
	s_waitcnt lgkmcnt(0)
	v_add_f32_e32 v3, v3, v17
	ds_bpermute_b32 v17, v14, v3
	v_cvt_pk_bf16_f32 v64, v76, v77
	v_cvt_pk_bf16_f32 v65, v78, v79
	global_store_dwordx2 v[34:35], v[68:69], off offset:1024
	global_store_dwordx2 v[34:35], v[64:65], off offset:1536
	s_waitcnt lgkmcnt(0)
	v_add_f32_e32 v3, v3, v17
	ds_bpermute_b32 v17, v15, v3
	s_waitcnt lgkmcnt(0)
	v_add_f32_e32 v3, v3, v17
	ds_bpermute_b32 v17, v16, v3
	s_and_saveexec_b64 s[0:1], vcc
	s_waitcnt lgkmcnt(0)
	v_add_f32_e32 v3, v3, v17
	v_cndmask_b32_e64 v3, 0, v3, s[4:5]
	v_lshl_add_u64 v[64:65], s[10:11], 0, v[4:5]
	global_store_dword v[64:65], v3, off
	s_or_b64 exec, exec, s[0:1]
	v_lshl_add_u64 v[4:5], v[4:5], 0, s[14:15]
	v_lshl_add_u64 v[6:7], v[6:7], 0, s[16:17]
	v_lshl_add_u64 v[80:81], v[8:9], 0, s[18:19]
	global_load_dwordx4 v[64:67], v[80:81], off offset:-3072
	global_load_dwordx4 v[68:71], v[80:81], off offset:-2048
	global_load_dwordx4 v[72:75], v[80:81], off offset:-1024
	global_load_dwordx4 v[76:79], v[80:81], off
	s_waitcnt vmcnt(9)
	v_mul_f32_e32 v3, v19, v19
	s_waitcnt lgkmcnt(0)
	v_mul_f32_e32 v17, v23, v23
	v_mul_f32_e32 v34, v27, v27
	v_fmac_f32_e32 v3, v18, v18
	v_fmac_f32_e32 v17, v22, v22
	v_mul_f32_e32 v35, v31, v31
	v_fmac_f32_e32 v34, v26, v26
	v_fmac_f32_e32 v3, v20, v20
	v_fmac_f32_e32 v17, v24, v24
	v_fmac_f32_e32 v35, v30, v30
	v_fmac_f32_e32 v34, v28, v28
	v_fmac_f32_e32 v3, v21, v21
	v_fmac_f32_e32 v17, v25, v25
	v_fmac_f32_e32 v35, v32, v32
	v_fmac_f32_e32 v34, v29, v29
	v_add_f32_e32 v3, v3, v17
	v_fmac_f32_e32 v35, v33, v33
	v_add_f32_e32 v3, v3, v34
	v_add_f32_e32 v3, v3, v35
	ds_bpermute_b32 v17, v11, v3
	v_lshl_add_u64 v[34:35], s[10:11], 0, v[6:7]
	v_add_co_u32_e64 v34, s[0:1], s3, v34
	v_cvt_pk_bf16_f32 v18, v18, v19
	s_waitcnt lgkmcnt(0)
	v_add_f32_e32 v3, v3, v17
	ds_bpermute_b32 v17, v12, v3
	v_addc_co_u32_e64 v35, s[0:1], 0, v35, s[0:1]
	v_cvt_pk_bf16_f32 v19, v20, v21
	v_cvt_pk_bf16_f32 v20, v22, v23
	s_waitcnt lgkmcnt(0)
	v_add_f32_e32 v3, v3, v17
	ds_bpermute_b32 v17, v13, v3
	v_cvt_pk_bf16_f32 v21, v24, v25
	v_cvt_pk_bf16_f32 v22, v26, v27
	global_store_dwordx2 v[34:35], v[18:19], off
	global_store_dwordx2 v[34:35], v[20:21], off offset:512
	v_cvt_pk_bf16_f32 v23, v28, v29
	s_waitcnt lgkmcnt(0)
	v_add_f32_e32 v3, v3, v17
	ds_bpermute_b32 v17, v14, v3
	v_cvt_pk_bf16_f32 v18, v30, v31
	v_cvt_pk_bf16_f32 v19, v32, v33
	global_store_dwordx2 v[34:35], v[22:23], off offset:1024
	global_store_dwordx2 v[34:35], v[18:19], off offset:1536
	s_waitcnt lgkmcnt(0)
	v_add_f32_e32 v3, v3, v17
	ds_bpermute_b32 v17, v15, v3
	s_waitcnt lgkmcnt(0)
	v_add_f32_e32 v3, v3, v17
	ds_bpermute_b32 v17, v16, v3
	s_and_saveexec_b64 s[0:1], vcc
	s_waitcnt lgkmcnt(0)
	v_add_f32_e32 v3, v3, v17
	v_cndmask_b32_e64 v3, 0, v3, s[4:5]
	v_lshl_add_u64 v[18:19], s[10:11], 0, v[4:5]
	global_store_dword v[18:19], v3, off
	s_or_b64 exec, exec, s[0:1]
	v_lshl_add_u64 v[4:5], v[4:5], 0, s[14:15]
	v_lshl_add_u64 v[6:7], v[6:7], 0, s[16:17]
	v_lshl_add_u64 v[8:9], v[80:81], 0, s[18:19]
	global_load_dwordx4 v[18:21], v[8:9], off offset:-3072
	global_load_dwordx4 v[22:25], v[8:9], off offset:-2048
	global_load_dwordx4 v[26:29], v[8:9], off offset:-1024
	global_load_dwordx4 v[30:33], v[8:9], off
	s_waitcnt vmcnt(9)
	v_mul_f32_e32 v3, v65, v65
	s_waitcnt lgkmcnt(0)
	v_mul_f32_e32 v17, v69, v69
	v_mul_f32_e32 v34, v73, v73
	v_fmac_f32_e32 v3, v64, v64
	v_fmac_f32_e32 v17, v68, v68
	v_mul_f32_e32 v35, v77, v77
	v_fmac_f32_e32 v34, v72, v72
	v_fmac_f32_e32 v3, v66, v66
	v_fmac_f32_e32 v17, v70, v70
	v_fmac_f32_e32 v35, v76, v76
	v_fmac_f32_e32 v34, v74, v74
	v_fmac_f32_e32 v3, v67, v67
	v_fmac_f32_e32 v17, v71, v71
	v_fmac_f32_e32 v35, v78, v78
	v_fmac_f32_e32 v34, v75, v75
	v_add_f32_e32 v3, v3, v17
	v_fmac_f32_e32 v35, v79, v79
	v_add_f32_e32 v3, v3, v34
	v_add_f32_e32 v3, v3, v35
	ds_bpermute_b32 v17, v11, v3
	v_lshl_add_u64 v[34:35], s[10:11], 0, v[6:7]
	v_add_co_u32_e64 v34, s[0:1], s3, v34
	v_cvt_pk_bf16_f32 v64, v64, v65
	s_waitcnt lgkmcnt(0)
	v_add_f32_e32 v3, v3, v17
	ds_bpermute_b32 v17, v12, v3
	v_addc_co_u32_e64 v35, s[0:1], 0, v35, s[0:1]
	v_cvt_pk_bf16_f32 v65, v66, v67
	v_cvt_pk_bf16_f32 v66, v68, v69
	s_waitcnt lgkmcnt(0)
	v_add_f32_e32 v3, v3, v17
	ds_bpermute_b32 v17, v13, v3
	v_cvt_pk_bf16_f32 v67, v70, v71
	v_cvt_pk_bf16_f32 v68, v72, v73
	global_store_dwordx2 v[34:35], v[64:65], off
	global_store_dwordx2 v[34:35], v[66:67], off offset:512
	v_cvt_pk_bf16_f32 v69, v74, v75
	s_waitcnt lgkmcnt(0)
	v_add_f32_e32 v3, v3, v17
	ds_bpermute_b32 v17, v14, v3
	v_cvt_pk_bf16_f32 v64, v76, v77
	v_cvt_pk_bf16_f32 v65, v78, v79
	global_store_dwordx2 v[34:35], v[68:69], off offset:1024
	global_store_dwordx2 v[34:35], v[64:65], off offset:1536
	s_waitcnt lgkmcnt(0)
	v_add_f32_e32 v3, v3, v17
	ds_bpermute_b32 v17, v15, v3
	s_waitcnt lgkmcnt(0)
	v_add_f32_e32 v3, v3, v17
	ds_bpermute_b32 v17, v16, v3
	s_and_saveexec_b64 s[0:1], vcc
	s_waitcnt lgkmcnt(0)
	v_add_f32_e32 v3, v3, v17
	v_cndmask_b32_e64 v3, 0, v3, s[4:5]
	v_lshl_add_u64 v[64:65], s[10:11], 0, v[4:5]
	global_store_dword v[64:65], v3, off
	s_or_b64 exec, exec, s[0:1]
	v_lshl_add_u64 v[4:5], v[4:5], 0, s[14:15]
	v_lshl_add_u64 v[6:7], v[6:7], 0, s[16:17]
	v_lshl_add_u64 v[80:81], v[8:9], 0, s[18:19]
	global_load_dwordx4 v[64:67], v[80:81], off offset:-3072
	global_load_dwordx4 v[68:71], v[80:81], off offset:-2048
	global_load_dwordx4 v[72:75], v[80:81], off offset:-1024
	global_load_dwordx4 v[76:79], v[80:81], off
	s_waitcnt vmcnt(9)
	v_mul_f32_e32 v3, v19, v19
	s_waitcnt lgkmcnt(0)
	v_mul_f32_e32 v17, v23, v23
	v_mul_f32_e32 v34, v27, v27
	v_fmac_f32_e32 v3, v18, v18
	v_fmac_f32_e32 v17, v22, v22
	v_mul_f32_e32 v35, v31, v31
	v_fmac_f32_e32 v34, v26, v26
	v_fmac_f32_e32 v3, v20, v20
	v_fmac_f32_e32 v17, v24, v24
	v_fmac_f32_e32 v35, v30, v30
	v_fmac_f32_e32 v34, v28, v28
	v_fmac_f32_e32 v3, v21, v21
	v_fmac_f32_e32 v17, v25, v25
	v_fmac_f32_e32 v35, v32, v32
	v_fmac_f32_e32 v34, v29, v29
	v_add_f32_e32 v3, v3, v17
	v_fmac_f32_e32 v35, v33, v33
	v_add_f32_e32 v3, v3, v34
	v_add_f32_e32 v3, v3, v35
	ds_bpermute_b32 v17, v11, v3
	v_lshl_add_u64 v[34:35], s[10:11], 0, v[6:7]
	v_add_co_u32_e64 v34, s[0:1], s3, v34
	v_cvt_pk_bf16_f32 v18, v18, v19
	s_waitcnt lgkmcnt(0)
	v_add_f32_e32 v3, v3, v17
	ds_bpermute_b32 v17, v12, v3
	v_addc_co_u32_e64 v35, s[0:1], 0, v35, s[0:1]
	v_cvt_pk_bf16_f32 v19, v20, v21
	v_cvt_pk_bf16_f32 v20, v22, v23
	s_waitcnt lgkmcnt(0)
	v_add_f32_e32 v3, v3, v17
	ds_bpermute_b32 v17, v13, v3
	v_cvt_pk_bf16_f32 v21, v24, v25
	v_cvt_pk_bf16_f32 v22, v26, v27
	global_store_dwordx2 v[34:35], v[18:19], off
	global_store_dwordx2 v[34:35], v[20:21], off offset:512
	v_cvt_pk_bf16_f32 v23, v28, v29
	s_waitcnt lgkmcnt(0)
	v_add_f32_e32 v3, v3, v17
	ds_bpermute_b32 v17, v14, v3
	v_cvt_pk_bf16_f32 v18, v30, v31
	v_cvt_pk_bf16_f32 v19, v32, v33
	global_store_dwordx2 v[34:35], v[22:23], off offset:1024
	global_store_dwordx2 v[34:35], v[18:19], off offset:1536
	s_waitcnt lgkmcnt(0)
	v_add_f32_e32 v3, v3, v17
	ds_bpermute_b32 v17, v15, v3
	s_waitcnt lgkmcnt(0)
	v_add_f32_e32 v3, v3, v17
	ds_bpermute_b32 v17, v16, v3
	s_and_saveexec_b64 s[0:1], vcc
	s_waitcnt lgkmcnt(0)
	v_add_f32_e32 v3, v3, v17
	v_cndmask_b32_e64 v3, 0, v3, s[4:5]
	v_lshl_add_u64 v[18:19], s[10:11], 0, v[4:5]
	global_store_dword v[18:19], v3, off
	s_or_b64 exec, exec, s[0:1]
	v_lshl_add_u64 v[4:5], v[4:5], 0, s[14:15]
	v_lshl_add_u64 v[6:7], v[6:7], 0, s[16:17]
	s_waitcnt vmcnt(5)
	v_mul_f32_e32 v3, v65, v65
	s_waitcnt lgkmcnt(0)
	v_mul_f32_e32 v17, v69, v69
	v_mul_f32_e32 v34, v73, v73
	v_fmac_f32_e32 v3, v64, v64
	v_fmac_f32_e32 v17, v68, v68
	v_mul_f32_e32 v35, v77, v77
	v_fmac_f32_e32 v34, v72, v72
	v_fmac_f32_e32 v3, v66, v66
	v_fmac_f32_e32 v17, v70, v70
	v_fmac_f32_e32 v35, v76, v76
	v_fmac_f32_e32 v34, v74, v74
	v_fmac_f32_e32 v3, v67, v67
	v_fmac_f32_e32 v17, v71, v71
	v_fmac_f32_e32 v35, v78, v78
	v_fmac_f32_e32 v34, v75, v75
	v_add_f32_e32 v3, v3, v17
	v_fmac_f32_e32 v35, v79, v79
	v_add_f32_e32 v3, v3, v34
	v_add_f32_e32 v3, v3, v35
	ds_bpermute_b32 v17, v11, v3
	v_lshl_add_u64 v[34:35], s[10:11], 0, v[6:7]
	v_add_co_u32_e64 v34, s[0:1], s3, v34
	v_cvt_pk_bf16_f32 v64, v64, v65
	s_waitcnt lgkmcnt(0)
	v_add_f32_e32 v3, v3, v17
	ds_bpermute_b32 v17, v12, v3
	v_addc_co_u32_e64 v35, s[0:1], 0, v35, s[0:1]
	v_cvt_pk_bf16_f32 v65, v66, v67
	v_cvt_pk_bf16_f32 v66, v68, v69
	s_waitcnt lgkmcnt(0)
	v_add_f32_e32 v3, v3, v17
	ds_bpermute_b32 v17, v13, v3
	v_cvt_pk_bf16_f32 v67, v70, v71
	v_cvt_pk_bf16_f32 v68, v72, v73
	global_store_dwordx2 v[34:35], v[64:65], off
	global_store_dwordx2 v[34:35], v[66:67], off offset:512
	v_cvt_pk_bf16_f32 v69, v74, v75
	s_waitcnt lgkmcnt(0)
	v_add_f32_e32 v3, v3, v17
	ds_bpermute_b32 v17, v14, v3
	v_cvt_pk_bf16_f32 v64, v76, v77
	v_cvt_pk_bf16_f32 v65, v78, v79
	global_store_dwordx2 v[34:35], v[68:69], off offset:1024
	global_store_dwordx2 v[34:35], v[64:65], off offset:1536
	s_waitcnt lgkmcnt(0)
	v_add_f32_e32 v3, v3, v17
	ds_bpermute_b32 v17, v15, v3
	s_waitcnt lgkmcnt(0)
	v_add_f32_e32 v3, v3, v17
	ds_bpermute_b32 v17, v16, v3
	s_and_saveexec_b64 s[0:1], vcc
	s_waitcnt lgkmcnt(0)
	v_add_f32_e32 v3, v3, v17
	v_cndmask_b32_e64 v3, 0, v3, s[4:5]
	v_lshl_add_u64 v[64:65], s[10:11], 0, v[4:5]
	global_store_dword v[64:65], v3, off
	s_or_b64 exec, exec, s[0:1]
